# phase 3: WGs 256..287 (CU partners of the dn_l1 scan WGs) take no SWA-side items; items re-partitioned over the other 448 WGs
# speedup vs baseline: 1.6437x; 1.0161x over previous
.LBB0_361:
	s_or_b64 exec, exec, s[0:1]
	v_readlane_b32 s2, v252, 0
	v_readlane_b32 s3, v252, 1
	s_add_u32 s0, s2, 0x880000
	s_addc_u32 s1, s3, 0
	v_writelane_b32 v250, s0, 13
	v_readlane_b32 s4, v252, 2
	s_waitcnt lgkmcnt(0)
	v_writelane_b32 v250, s1, 14
	s_add_u32 s0, s2, 0xe80000
	s_addc_u32 s1, s3, 0
	v_writelane_b32 v250, s0, 15
	s_barrier
	s_nop 0
	v_writelane_b32 v250, s1, 16
	s_add_u32 s0, s2, 0x7c4b700
	s_addc_u32 s1, s3, 0
	v_writelane_b32 v250, s0, 17
	v_readlane_b32 s5, v252, 3
	s_nop 0
	v_writelane_b32 v250, s1, 18
	s_not_b32 s0, s94
	s_add_i32 s0, s4, s0
	s_add_u32 s76, s2, 0x7c4bb00
	s_addc_u32 s77, s3, 0
	v_writelane_b32 v250, s0, 19
	s_cmp_gt_i32 s94, 31
	s_mov_b64 s[0:1], -1
	s_cbranch_scc0 .LBB0_475
	v_readlane_b32 s0, v252, 2
	s_sub_i32 s91, s94, 0x100
	s_cmp_lt_u32 s91, 32
	s_cbranch_scc1 .LBB0_474
	s_sub_i32 s91, s0, 64
	s_cmpk_gt_u32 s94, 0xff
	s_cselect_b32 s1, 64, 32
	s_sub_i32 s92, s94, s1
	v_writelane_b32 v250, s31, 20
	s_cmpk_gt_u32 s92, 0x40f
	v_writelane_b32 v250, s30, 22
	v_readlane_b32 s1, v252, 3
	s_cbranch_scc1 .LBB0_367
	v_readlane_b32 s0, v252, 37
	v_mbcnt_hi_u32_b32 v165, -1, v219
	v_readlane_b32 s1, v252, 38
	v_and_b32_e32 v0, 64, v165
	v_mov_b32_e32 v156, 0x200f
	s_movk_i32 s17, 0x1a00
	v_mov_b64_e32 v[146:147], s[0:1]
	s_mov_b32 s3, 0
	v_mov_b32_e32 v149, 0
	s_movk_i32 s33, 0x80
	s_mov_b32 s16, 0x3e000000
	v_mov_b32_e32 v157, 0xf149f2ca
	v_not_b32_e32 v158, 16
	v_not_b32_e32 v159, 17
	v_not_b32_e32 v160, 18
	v_not_b32_e32 v161, 23
	v_not_b32_e32 v162, 24
	v_not_b32_e32 v163, 25
	v_not_b32_e32 v164, 26
	v_xor_b32_e32 v166, 32, v165
	v_add_u32_e32 v167, 64, v0
	s_mov_b32 s38, 0xefa18f08
	s_mov_b64 s[18:19], 0x106000
	s_mov_b32 s39, 0x106000
	s_movk_i32 s40, 0x7fff
	s_mov_b32 s41, 0x7060302
	v_mov_b32_e32 v168, 1
	s_mov_b32 s42, s92
	s_branch .LBB0_365

.LBB0_367:
	v_writelane_b32 v250, s77, 24
	v_writelane_b32 v250, s76, 26
	s_nop 0
	s_sub_i32 s0, s91, s92
	s_add_i32 s0, s0, -1
	s_cmpk_gt_i32 s0, 0x7f
	s_cbranch_scc1 .LBB0_453
	v_readlane_b32 s0, v252, 13
	v_readlane_b32 s14, v252, 27
	v_readlane_b32 s15, v252, 28
	s_add_u32 s0, s14, 0x4249000
	s_addc_u32 s90, s15, 0
	s_add_u32 s33, s14, 0x4a49000
	v_writelane_b32 v250, s0, 28
	s_addc_u32 s0, s15, 0
	v_readlane_b32 s1, v252, 14
	v_readlane_b32 s2, v252, 15
	v_readlane_b32 s3, v252, 16
	v_writelane_b32 v250, s0, 30
	v_readlane_b32 s2, v252, 2
	s_sub_i32 s0, s91, s92
	s_add_i32 s93, s0, 0x401f
	s_add_i32 s0, s0, -1
	s_movk_i32 s94, 0xff
	s_movk_i32 s95, 0x204
	v_mov_b32_e32 v61, 0
	v_mov_b32_e32 v128, 0x11200
	v_mov_b32_e32 v129, 0x10200
	v_mbcnt_hi_u32_b32 v130, -1, v219
	v_mov_b32_e32 v131, 1
	s_mov_b32 s16, s0
	v_readlane_b32 s4, v252, 17
	v_readlane_b32 s5, v252, 18
	v_readlane_b32 s6, v252, 19
	v_readlane_b32 s7, v252, 20
	v_readlane_b32 s8, v252, 21
	v_readlane_b32 s9, v252, 22
	v_readlane_b32 s10, v252, 23
	v_readlane_b32 s11, v252, 24
	v_readlane_b32 s12, v252, 25
	v_readlane_b32 s13, v252, 26
	v_readlane_b32 s1, v250, 10
	v_readlane_b32 s3, v252, 3

.LBB0_453:
	s_abs_i32 s0, s91
	v_cvt_f32_u32_e32 v0, s0
	s_sub_i32 s3, 0, s0
	v_readlane_b32 s94, v250, 9
	s_add_i32 s1, s92, 0xc8
	v_rcp_iflag_f32_e32 v0, v0
	s_ashr_i32 s2, s1, 31
	s_abs_i32 s1, s1
	v_readlane_b32 s30, v250, 22
	v_mul_f32_e32 v0, 0x4f7ffffe, v0
	v_cvt_u32_f32_e32 v0, v0
	v_readlane_b32 s31, v250, 20
	v_readlane_b32 s76, v250, 26
	v_readlane_b32 s77, v250, 24
	v_readfirstlane_b32 s4, v0
	s_mul_i32 s3, s3, s4
	s_mul_hi_u32 s3, s4, s3
	s_add_i32 s4, s4, s3
	s_mul_hi_u32 s3, s1, s4
	s_mul_i32 s3, s3, s0
	s_sub_i32 s1, s1, s3
	s_sub_i32 s3, s1, s0
	s_cmp_ge_u32 s1, s0
	s_cselect_b32 s1, s3, s1
	s_sub_i32 s3, s1, s0
	s_cmp_ge_u32 s1, s0
	s_cselect_b32 s0, s3, s1
	s_xor_b32 s0, s0, s2
	s_sub_i32 s2, s0, s2
	s_cmpk_gt_i32 s2, 0x1ff
	v_readlane_b32 s95, v250, 10
	s_cbranch_scc1 .LBB0_467
	v_readlane_b32 s0, v252, 0
	v_readlane_b32 s1, v252, 1
	s_add_u32 s14, s0, 0x12ac100
	v_readlane_b32 s40, v252, 13
	s_addc_u32 s15, s1, 0
	v_readlane_b32 s54, v252, 27
	v_readlane_b32 s55, v252, 28
	s_add_u32 s16, s54, 0x5249000
	s_addc_u32 s17, s55, 0
	s_add_u32 s18, s54, 0x5489000
	s_addc_u32 s19, s55, 0
	s_mov_b32 s20, 0x3fb8aa3b
	s_mov_b32 s21, 0xc2ce8ed0
	s_mov_b32 s33, 0x42b17218
	v_mov_b32_e32 v112, 0x3ecc95a3
	s_mov_b32 s38, 0x800000
	v_mov_b32_e32 v113, 0x7f800000
	v_mov_b32_e32 v69, 0
	v_mov_b32_e32 v70, 0x3f317218
	v_readlane_b32 s41, v252, 14
	v_readlane_b32 s42, v252, 15
	v_readlane_b32 s43, v252, 16
	v_readlane_b32 s44, v252, 17
	v_readlane_b32 s45, v252, 18
	v_readlane_b32 s46, v252, 19
	v_readlane_b32 s47, v252, 20
	v_readlane_b32 s48, v252, 21
	v_readlane_b32 s49, v252, 22
	v_readlane_b32 s50, v252, 23
	v_readlane_b32 s51, v252, 24
	v_readlane_b32 s52, v252, 25
	v_readlane_b32 s53, v252, 26
	s_branch .LBB0_456

.LBB0_467:
	s_cmpk_gt_i32 s92, 0x3ff
	s_cbranch_scc1 .LBB0_474
	s_lshl_b32 s4, s92, 2
	s_add_i32 s4, s4, 0xfffff400
	s_lshl_b32 s5, s91, 2
	s_lshl_b32 s6, s92, 6
	s_add_i32 s6, s6, 0xffff4000
	s_lshl_b32 s7, s91, 6
	s_mov_b32 s1, 0
	v_mov_b32_e32 v1, 0
	s_movk_i32 s8, 0x104
	s_movk_i32 s9, 0x7fff
	s_movk_i32 s10, 0x3040
	s_branch .LBB0_470
